# baseline (speedup 1.0000x reference)
; __device__ __forceinline__ u32 pack2(float a, float b) { return (u32)f2bf(a) | ((u32)f2bf(b) << 16); }
; __device__ __forceinline__ float sigmoidf_(float x) { return __builtin_amdgcn_rcpf(1.f + __expf(-x)); }
; __device__ __forceinline__ void gemm_tile(const GemmArgs& ga, int wgid, int next_wgid, bool prefetched, u16* shm, unsigned char* ws, int wv_) {
;     ...
;   if (epi == EPI_SWIGLU) {
;     const int oc = pn * HALF + (wc * 16 + fr) * 2;
;     float sc[2][4][4];
;     _Pragma("unroll") for (int ai = 0; ai < 2; ++ai)
;       _Pragma("unroll") for (int m = 0; m < 4; ++m)
;         _Pragma("unroll") for (int j = 0; j < 4; ++j) sc[ai][m][j] = e_ss[rbase + ai * HALF + m * 16 + j];
;     _Pragma("unroll") for (int ai = 0; ai < 2; ++ai)
;       _Pragma("unroll") for (int m = 0; m < 4; ++m)
;         _Pragma("unroll") for (int j = 0; j < 4; ++j) {
;           int row = rbase + ai * HALF + m * 16 + j;
;           float s = rsqrtf(sc[ai][m][j] * (1.f / D_) + 1e-6f);
;           float h2[2];
;           _Pragma("unroll") for (int n = 0; n < 2; ++n) {
;             float a1 = acc[ai][0][m][n][j] * s, a3 = acc[ai][1][m][n][j] * s;
;             h2[n] = a1 * sigmoidf_(a1) * a3;
;           }
;           *(u32*)(e_outb + (size_t)row * F_ + oc) = pack2(h2[0], h2[1]);
;         }
.Lsswd_s:
	v_pk_fma_f32 v[0:1], v[208:209], s[12:13], v[130:131] op_sel_hi:[1,0,0]
	v_add_u32_e32 v8, 0, v168
	v_add_u32_e32 v9, 1, v168
	v_rsq_f32_e32 v0, v0
	v_rsq_f32_e32 v1, v1
	v_mad_i64_i32 v[10:11], s[2:3], v8, s8, v[128:129]
	v_mad_i64_i32 v[2:3], s[2:3], v9, s8, v[128:129]
	v_pk_mul_f32 v[16:17], v[116:117], v[0:1]
	v_pk_mul_f32 v[18:19], v[112:113], v[0:1]
	v_pk_mul_f32 v[136:137], v[124:125], v[0:1]
	v_pk_mul_f32 v[138:139], v[120:121], v[0:1]
	v_mul_f32_e32 v140, 0xbfb8aa3b, v16
	v_mul_f32_e32 v141, 0xbfb8aa3b, v17
	v_mul_f32_e32 v142, 0xbfb8aa3b, v18
	v_mul_f32_e32 v143, 0xbfb8aa3b, v19
	v_exp_f32_e32 v140, v140
	v_exp_f32_e32 v141, v141
	v_exp_f32_e32 v142, v142
	v_exp_f32_e32 v143, v143
	v_add_f32_e32 v140, 1.0, v140
	v_add_f32_e32 v141, 1.0, v141
	v_add_f32_e32 v142, 1.0, v142
	v_add_f32_e32 v143, 1.0, v143
	v_rcp_f32_e32 v140, v140
	v_rcp_f32_e32 v141, v141
	v_rcp_f32_e32 v142, v142
	v_rcp_f32_e32 v143, v143
	s_nop 0
	v_pk_mul_f32 v[16:17], v[16:17], v[140:141]
	v_pk_mul_f32 v[18:19], v[18:19], v[142:143]
	v_pk_mul_f32 v[16:17], v[136:137], v[16:17]
	v_pk_mul_f32 v[18:19], v[138:139], v[18:19]
	v_cvt_pk_bf16_f32 v8, v16, v18
	v_cvt_pk_bf16_f32 v9, v17, v19
	global_store_dword v[10:11], v8, off
	global_store_dword v[2:3], v9, off
	v_pk_fma_f32 v[0:1], v[210:211], s[12:13], v[130:131] op_sel_hi:[1,0,0]
	v_add_u32_e32 v8, 2, v168
	v_add_u32_e32 v9, 3, v168
	v_rsq_f32_e32 v0, v0
	v_rsq_f32_e32 v1, v1
	v_mad_i64_i32 v[10:11], s[2:3], v8, s8, v[128:129]
	v_mad_i64_i32 v[2:3], s[2:3], v9, s8, v[128:129]
	v_pk_mul_f32 v[16:17], v[118:119], v[0:1]
	v_pk_mul_f32 v[18:19], v[114:115], v[0:1]
	v_pk_mul_f32 v[136:137], v[126:127], v[0:1]
	v_pk_mul_f32 v[138:139], v[122:123], v[0:1]
	v_mul_f32_e32 v140, 0xbfb8aa3b, v16
	v_mul_f32_e32 v141, 0xbfb8aa3b, v17
	v_mul_f32_e32 v142, 0xbfb8aa3b, v18
	v_mul_f32_e32 v143, 0xbfb8aa3b, v19
	v_exp_f32_e32 v140, v140
	v_exp_f32_e32 v141, v141
	v_exp_f32_e32 v142, v142
	v_exp_f32_e32 v143, v143
	v_add_f32_e32 v140, 1.0, v140
	v_add_f32_e32 v141, 1.0, v141
	v_add_f32_e32 v142, 1.0, v142
	v_add_f32_e32 v143, 1.0, v143
	v_rcp_f32_e32 v140, v140
	v_rcp_f32_e32 v141, v141
	v_rcp_f32_e32 v142, v142
	v_rcp_f32_e32 v143, v143
	s_nop 0
	v_pk_mul_f32 v[16:17], v[16:17], v[140:141]
	v_pk_mul_f32 v[18:19], v[18:19], v[142:143]
	v_pk_mul_f32 v[16:17], v[136:137], v[16:17]
	v_pk_mul_f32 v[18:19], v[138:139], v[18:19]
	v_cvt_pk_bf16_f32 v8, v16, v18
	v_cvt_pk_bf16_f32 v9, v17, v19
	global_store_dword v[10:11], v8, off
	global_store_dword v[2:3], v9, off
	v_pk_fma_f32 v[0:1], v[212:213], s[12:13], v[130:131] op_sel_hi:[1,0,0]
	v_add_u32_e32 v8, 16, v168
	v_add_u32_e32 v9, 17, v168
	v_rsq_f32_e32 v0, v0
	v_rsq_f32_e32 v1, v1
	v_mad_i64_i32 v[10:11], s[2:3], v8, s8, v[128:129]
	v_mad_i64_i32 v[2:3], s[2:3], v9, s8, v[128:129]
	v_pk_mul_f32 v[16:17], v[100:101], v[0:1]
	v_pk_mul_f32 v[18:19], v[96:97], v[0:1]
	v_pk_mul_f32 v[136:137], v[108:109], v[0:1]
	v_pk_mul_f32 v[138:139], v[104:105], v[0:1]
	v_mul_f32_e32 v140, 0xbfb8aa3b, v16
	v_mul_f32_e32 v141, 0xbfb8aa3b, v17
	v_mul_f32_e32 v142, 0xbfb8aa3b, v18
	v_mul_f32_e32 v143, 0xbfb8aa3b, v19
	v_exp_f32_e32 v140, v140
	v_exp_f32_e32 v141, v141
	v_exp_f32_e32 v142, v142
	v_exp_f32_e32 v143, v143
	v_add_f32_e32 v140, 1.0, v140
	v_add_f32_e32 v141, 1.0, v141
	v_add_f32_e32 v142, 1.0, v142
	v_add_f32_e32 v143, 1.0, v143
	v_rcp_f32_e32 v140, v140
	v_rcp_f32_e32 v141, v141
	v_rcp_f32_e32 v142, v142
	v_rcp_f32_e32 v143, v143
	s_nop 0
	v_pk_mul_f32 v[16:17], v[16:17], v[140:141]
	v_pk_mul_f32 v[18:19], v[18:19], v[142:143]
	v_pk_mul_f32 v[16:17], v[136:137], v[16:17]
	v_pk_mul_f32 v[18:19], v[138:139], v[18:19]
	v_cvt_pk_bf16_f32 v8, v16, v18
	v_cvt_pk_bf16_f32 v9, v17, v19
	global_store_dword v[10:11], v8, off
	global_store_dword v[2:3], v9, off
	v_pk_fma_f32 v[0:1], v[214:215], s[12:13], v[130:131] op_sel_hi:[1,0,0]
	v_add_u32_e32 v8, 18, v168
	v_add_u32_e32 v9, 19, v168
	v_rsq_f32_e32 v0, v0
	v_rsq_f32_e32 v1, v1
	v_mad_i64_i32 v[10:11], s[2:3], v8, s8, v[128:129]
	v_mad_i64_i32 v[2:3], s[2:3], v9, s8, v[128:129]
	v_pk_mul_f32 v[16:17], v[102:103], v[0:1]
	v_pk_mul_f32 v[18:19], v[98:99], v[0:1]
	v_pk_mul_f32 v[136:137], v[110:111], v[0:1]
	v_pk_mul_f32 v[138:139], v[106:107], v[0:1]
	v_mul_f32_e32 v140, 0xbfb8aa3b, v16
	v_mul_f32_e32 v141, 0xbfb8aa3b, v17
	v_mul_f32_e32 v142, 0xbfb8aa3b, v18
	v_mul_f32_e32 v143, 0xbfb8aa3b, v19
	v_exp_f32_e32 v140, v140
	v_exp_f32_e32 v141, v141
	v_exp_f32_e32 v142, v142
	v_exp_f32_e32 v143, v143
	v_add_f32_e32 v140, 1.0, v140
	v_add_f32_e32 v141, 1.0, v141
	v_add_f32_e32 v142, 1.0, v142
	v_add_f32_e32 v143, 1.0, v143
	v_rcp_f32_e32 v140, v140
	v_rcp_f32_e32 v141, v141
	v_rcp_f32_e32 v142, v142
	v_rcp_f32_e32 v143, v143
	s_nop 0
	v_pk_mul_f32 v[16:17], v[16:17], v[140:141]
	v_pk_mul_f32 v[18:19], v[18:19], v[142:143]
	v_pk_mul_f32 v[16:17], v[136:137], v[16:17]
	v_pk_mul_f32 v[18:19], v[138:139], v[18:19]
	v_cvt_pk_bf16_f32 v8, v16, v18
	v_cvt_pk_bf16_f32 v9, v17, v19
	global_store_dword v[10:11], v8, off
	global_store_dword v[2:3], v9, off
	v_pk_fma_f32 v[0:1], v[216:217], s[12:13], v[130:131] op_sel_hi:[1,0,0]
	v_add_u32_e32 v8, 32, v168
	v_add_u32_e32 v9, 33, v168
	v_rsq_f32_e32 v0, v0
	v_rsq_f32_e32 v1, v1
	v_mad_i64_i32 v[10:11], s[2:3], v8, s8, v[128:129]
	v_mad_i64_i32 v[2:3], s[2:3], v9, s8, v[128:129]
	v_pk_mul_f32 v[16:17], v[84:85], v[0:1]
	v_pk_mul_f32 v[18:19], v[80:81], v[0:1]
	v_pk_mul_f32 v[136:137], v[92:93], v[0:1]
	v_pk_mul_f32 v[138:139], v[88:89], v[0:1]
	v_mul_f32_e32 v140, 0xbfb8aa3b, v16
	v_mul_f32_e32 v141, 0xbfb8aa3b, v17
	v_mul_f32_e32 v142, 0xbfb8aa3b, v18
	v_mul_f32_e32 v143, 0xbfb8aa3b, v19
	v_exp_f32_e32 v140, v140
; __device__ __forceinline__ u32 pack2(float a, float b) { return (u32)f2bf(a) | ((u32)f2bf(b) << 16); }
; __device__ __forceinline__ float sigmoidf_(float x) { return __builtin_amdgcn_rcpf(1.f + __expf(-x)); }
; __device__ __forceinline__ void gemm_tile(const GemmArgs& ga, int wgid, int next_wgid, bool prefetched, u16* shm, unsigned char* ws, int wv_) {
;     ...
;   if (epi == EPI_SWIGLU) {
;     const int oc = pn * HALF + (wc * 16 + fr) * 2;
;     float sc[2][4][4];
;     _Pragma("unroll") for (int ai = 0; ai < 2; ++ai)
;       _Pragma("unroll") for (int m = 0; m < 4; ++m)
;         _Pragma("unroll") for (int j = 0; j < 4; ++j) sc[ai][m][j] = e_ss[rbase + ai * HALF + m * 16 + j];
;     _Pragma("unroll") for (int ai = 0; ai < 2; ++ai)
;       _Pragma("unroll") for (int m = 0; m < 4; ++m)
;         _Pragma("unroll") for (int j = 0; j < 4; ++j) {
;           int row = rbase + ai * HALF + m * 16 + j;
;           float s = rsqrtf(sc[ai][m][j] * (1.f / D_) + 1e-6f);
;           float h2[2];
;           _Pragma("unroll") for (int n = 0; n < 2; ++n) {
;             float a1 = acc[ai][0][m][n][j] * s, a3 = acc[ai][1][m][n][j] * s;
;             h2[n] = a1 * sigmoidf_(a1) * a3;
;           }
;           *(u32*)(e_outb + (size_t)row * F_ + oc) = pack2(h2[0], h2[1]);
;         }
	v_exp_f32_e32 v141, v141
	v_exp_f32_e32 v142, v142
	v_exp_f32_e32 v143, v143
	v_add_f32_e32 v140, 1.0, v140
	v_add_f32_e32 v141, 1.0, v141
	v_add_f32_e32 v142, 1.0, v142
	v_add_f32_e32 v143, 1.0, v143
	v_rcp_f32_e32 v140, v140
	v_rcp_f32_e32 v141, v141
	v_rcp_f32_e32 v142, v142
	v_rcp_f32_e32 v143, v143
	s_nop 0
	v_pk_mul_f32 v[16:17], v[16:17], v[140:141]
	v_pk_mul_f32 v[18:19], v[18:19], v[142:143]
	v_pk_mul_f32 v[16:17], v[136:137], v[16:17]
	v_pk_mul_f32 v[18:19], v[138:139], v[18:19]
	v_cvt_pk_bf16_f32 v8, v16, v18
	v_cvt_pk_bf16_f32 v9, v17, v19
	global_store_dword v[10:11], v8, off
	global_store_dword v[2:3], v9, off
	v_pk_fma_f32 v[0:1], v[218:219], s[12:13], v[130:131] op_sel_hi:[1,0,0]
	v_add_u32_e32 v8, 34, v168
	v_add_u32_e32 v9, 35, v168
	v_rsq_f32_e32 v0, v0
	v_rsq_f32_e32 v1, v1
	v_mad_i64_i32 v[10:11], s[2:3], v8, s8, v[128:129]
	v_mad_i64_i32 v[2:3], s[2:3], v9, s8, v[128:129]
	v_pk_mul_f32 v[16:17], v[86:87], v[0:1]
	v_pk_mul_f32 v[18:19], v[82:83], v[0:1]
	v_pk_mul_f32 v[136:137], v[94:95], v[0:1]
	v_pk_mul_f32 v[138:139], v[90:91], v[0:1]
	v_mul_f32_e32 v140, 0xbfb8aa3b, v16
	v_mul_f32_e32 v141, 0xbfb8aa3b, v17
	v_mul_f32_e32 v142, 0xbfb8aa3b, v18
	v_mul_f32_e32 v143, 0xbfb8aa3b, v19
	v_exp_f32_e32 v140, v140
	v_exp_f32_e32 v141, v141
	v_exp_f32_e32 v142, v142
	v_exp_f32_e32 v143, v143
	v_add_f32_e32 v140, 1.0, v140
	v_add_f32_e32 v141, 1.0, v141
	v_add_f32_e32 v142, 1.0, v142
	v_add_f32_e32 v143, 1.0, v143
	v_rcp_f32_e32 v140, v140
	v_rcp_f32_e32 v141, v141
	v_rcp_f32_e32 v142, v142
	v_rcp_f32_e32 v143, v143
	s_nop 0
	v_pk_mul_f32 v[16:17], v[16:17], v[140:141]
	v_pk_mul_f32 v[18:19], v[18:19], v[142:143]
	v_pk_mul_f32 v[16:17], v[136:137], v[16:17]
	v_pk_mul_f32 v[18:19], v[138:139], v[18:19]
	v_cvt_pk_bf16_f32 v8, v16, v18
	v_cvt_pk_bf16_f32 v9, v17, v19
	global_store_dword v[10:11], v8, off
	global_store_dword v[2:3], v9, off
	v_pk_fma_f32 v[0:1], v[220:221], s[12:13], v[130:131] op_sel_hi:[1,0,0]
	v_add_u32_e32 v8, 48, v168
	v_add_u32_e32 v9, 49, v168
	v_rsq_f32_e32 v0, v0
	v_rsq_f32_e32 v1, v1
	v_mad_i64_i32 v[10:11], s[2:3], v8, s8, v[128:129]
	v_mad_i64_i32 v[2:3], s[2:3], v9, s8, v[128:129]
	v_pk_mul_f32 v[16:17], v[68:69], v[0:1]
	v_pk_mul_f32 v[18:19], v[64:65], v[0:1]
	v_pk_mul_f32 v[136:137], v[76:77], v[0:1]
	v_pk_mul_f32 v[138:139], v[72:73], v[0:1]
	v_mul_f32_e32 v140, 0xbfb8aa3b, v16
	v_mul_f32_e32 v141, 0xbfb8aa3b, v17
	v_mul_f32_e32 v142, 0xbfb8aa3b, v18
	v_mul_f32_e32 v143, 0xbfb8aa3b, v19
	v_exp_f32_e32 v140, v140
	v_exp_f32_e32 v141, v141
	v_exp_f32_e32 v142, v142
	v_exp_f32_e32 v143, v143
	v_add_f32_e32 v140, 1.0, v140
	v_add_f32_e32 v141, 1.0, v141
	v_add_f32_e32 v142, 1.0, v142
	v_add_f32_e32 v143, 1.0, v143
	v_rcp_f32_e32 v140, v140
	v_rcp_f32_e32 v141, v141
	v_rcp_f32_e32 v142, v142
	v_rcp_f32_e32 v143, v143
	s_nop 0
	v_pk_mul_f32 v[16:17], v[16:17], v[140:141]
	v_pk_mul_f32 v[18:19], v[18:19], v[142:143]
	v_pk_mul_f32 v[16:17], v[136:137], v[16:17]
	v_pk_mul_f32 v[18:19], v[138:139], v[18:19]
	v_cvt_pk_bf16_f32 v8, v16, v18
	v_cvt_pk_bf16_f32 v9, v17, v19
	global_store_dword v[10:11], v8, off
	global_store_dword v[2:3], v9, off
	v_pk_fma_f32 v[0:1], v[222:223], s[12:13], v[130:131] op_sel_hi:[1,0,0]
	v_add_u32_e32 v8, 50, v168
	v_add_u32_e32 v9, 51, v168
	v_rsq_f32_e32 v0, v0
	v_rsq_f32_e32 v1, v1
	v_mad_i64_i32 v[10:11], s[2:3], v8, s8, v[128:129]
	v_mad_i64_i32 v[2:3], s[2:3], v9, s8, v[128:129]
	v_pk_mul_f32 v[16:17], v[70:71], v[0:1]
	v_pk_mul_f32 v[18:19], v[66:67], v[0:1]
	v_pk_mul_f32 v[136:137], v[78:79], v[0:1]
	v_pk_mul_f32 v[138:139], v[74:75], v[0:1]
	v_mul_f32_e32 v140, 0xbfb8aa3b, v16
	v_mul_f32_e32 v141, 0xbfb8aa3b, v17
	v_mul_f32_e32 v142, 0xbfb8aa3b, v18
	v_mul_f32_e32 v143, 0xbfb8aa3b, v19
	v_exp_f32_e32 v140, v140
	v_exp_f32_e32 v141, v141
	v_exp_f32_e32 v142, v142
	v_exp_f32_e32 v143, v143
	v_add_f32_e32 v140, 1.0, v140
	v_add_f32_e32 v141, 1.0, v141
	v_add_f32_e32 v142, 1.0, v142
	v_add_f32_e32 v143, 1.0, v143
	v_rcp_f32_e32 v140, v140
	v_rcp_f32_e32 v141, v141
	v_rcp_f32_e32 v142, v142
	v_rcp_f32_e32 v143, v143
	s_nop 0
	v_pk_mul_f32 v[16:17], v[16:17], v[140:141]
	v_pk_mul_f32 v[18:19], v[18:19], v[142:143]
	v_pk_mul_f32 v[16:17], v[136:137], v[16:17]
	v_pk_mul_f32 v[18:19], v[138:139], v[18:19]
	v_cvt_pk_bf16_f32 v8, v16, v18
	v_cvt_pk_bf16_f32 v9, v17, v19
	global_store_dword v[10:11], v8, off
	global_store_dword v[2:3], v9, off
	v_pk_fma_f32 v[0:1], v[224:225], s[12:13], v[130:131] op_sel_hi:[1,0,0]
	v_add_u32_e32 v8, 0x80, v168
	v_add_u32_e32 v9, 0x81, v168
	v_rsq_f32_e32 v0, v0
	v_rsq_f32_e32 v1, v1
	v_mad_i64_i32 v[10:11], s[2:3], v8, s8, v[128:129]
	v_mad_i64_i32 v[2:3], s[2:3], v9, s8, v[128:129]
	v_pk_mul_f32 v[16:17], v[52:53], v[0:1]
	v_pk_mul_f32 v[18:19], v[48:49], v[0:1]
	v_pk_mul_f32 v[136:137], v[60:61], v[0:1]
	v_pk_mul_f32 v[138:139], v[56:57], v[0:1]
	v_mul_f32_e32 v140, 0xbfb8aa3b, v16
	v_mul_f32_e32 v141, 0xbfb8aa3b, v17
	v_mul_f32_e32 v142, 0xbfb8aa3b, v18
	v_mul_f32_e32 v143, 0xbfb8aa3b, v19
	v_exp_f32_e32 v140, v140
	v_exp_f32_e32 v141, v141
	v_exp_f32_e32 v142, v142
	v_exp_f32_e32 v143, v143
	v_add_f32_e32 v140, 1.0, v140
	v_add_f32_e32 v141, 1.0, v141
	v_add_f32_e32 v142, 1.0, v142
	v_add_f32_e32 v143, 1.0, v143
	v_rcp_f32_e32 v140, v140
	v_rcp_f32_e32 v141, v141
	v_rcp_f32_e32 v142, v142
	v_rcp_f32_e32 v143, v143
	s_nop 0
	v_pk_mul_f32 v[16:17], v[16:17], v[140:141]
	v_pk_mul_f32 v[18:19], v[18:19], v[142:143]
	v_pk_mul_f32 v[16:17], v[136:137], v[16:17]
	v_pk_mul_f32 v[18:19], v[138:139], v[18:19]
	v_cvt_pk_bf16_f32 v8, v16, v18
	v_cvt_pk_bf16_f32 v9, v17, v19
	global_store_dword v[10:11], v8, off
	global_store_dword v[2:3], v9, off
; __device__ __forceinline__ u32 pack2(float a, float b) { return (u32)f2bf(a) | ((u32)f2bf(b) << 16); }
; __device__ __forceinline__ float sigmoidf_(float x) { return __builtin_amdgcn_rcpf(1.f + __expf(-x)); }
; __device__ __forceinline__ void gemm_tile(const GemmArgs& ga, int wgid, int next_wgid, bool prefetched, u16* shm, unsigned char* ws, int wv_) {
;     ...
;   if (epi == EPI_SWIGLU) {
;     const int oc = pn * HALF + (wc * 16 + fr) * 2;
;     float sc[2][4][4];
;     _Pragma("unroll") for (int ai = 0; ai < 2; ++ai)
;       _Pragma("unroll") for (int m = 0; m < 4; ++m)
;         _Pragma("unroll") for (int j = 0; j < 4; ++j) sc[ai][m][j] = e_ss[rbase + ai * HALF + m * 16 + j];
;     _Pragma("unroll") for (int ai = 0; ai < 2; ++ai)
;       _Pragma("unroll") for (int m = 0; m < 4; ++m)
;         _Pragma("unroll") for (int j = 0; j < 4; ++j) {
;           int row = rbase + ai * HALF + m * 16 + j;
;           float s = rsqrtf(sc[ai][m][j] * (1.f / D_) + 1e-6f);
;           float h2[2];
;           _Pragma("unroll") for (int n = 0; n < 2; ++n) {
;             float a1 = acc[ai][0][m][n][j] * s, a3 = acc[ai][1][m][n][j] * s;
;             h2[n] = a1 * sigmoidf_(a1) * a3;
;           }
;           *(u32*)(e_outb + (size_t)row * F_ + oc) = pack2(h2[0], h2[1]);
;         }
	v_pk_fma_f32 v[0:1], v[226:227], s[12:13], v[130:131] op_sel_hi:[1,0,0]
	v_add_u32_e32 v8, 0x82, v168
	v_add_u32_e32 v9, 0x83, v168
	v_rsq_f32_e32 v0, v0
	v_rsq_f32_e32 v1, v1
	v_mad_i64_i32 v[10:11], s[2:3], v8, s8, v[128:129]
	v_mad_i64_i32 v[2:3], s[2:3], v9, s8, v[128:129]
	v_pk_mul_f32 v[16:17], v[54:55], v[0:1]
	v_pk_mul_f32 v[18:19], v[50:51], v[0:1]
	v_pk_mul_f32 v[136:137], v[62:63], v[0:1]
	v_pk_mul_f32 v[138:139], v[58:59], v[0:1]
	v_mul_f32_e32 v140, 0xbfb8aa3b, v16
	v_mul_f32_e32 v141, 0xbfb8aa3b, v17
	v_mul_f32_e32 v142, 0xbfb8aa3b, v18
	v_mul_f32_e32 v143, 0xbfb8aa3b, v19
	v_exp_f32_e32 v140, v140
	v_exp_f32_e32 v141, v141
	v_exp_f32_e32 v142, v142
	v_exp_f32_e32 v143, v143
	v_add_f32_e32 v140, 1.0, v140
	v_add_f32_e32 v141, 1.0, v141
	v_add_f32_e32 v142, 1.0, v142
	v_add_f32_e32 v143, 1.0, v143
	v_rcp_f32_e32 v140, v140
	v_rcp_f32_e32 v141, v141
	v_rcp_f32_e32 v142, v142
	v_rcp_f32_e32 v143, v143
	s_nop 0
	v_pk_mul_f32 v[16:17], v[16:17], v[140:141]
	v_pk_mul_f32 v[18:19], v[18:19], v[142:143]
	v_pk_mul_f32 v[16:17], v[136:137], v[16:17]
	v_pk_mul_f32 v[18:19], v[138:139], v[18:19]
	v_cvt_pk_bf16_f32 v8, v16, v18
	v_cvt_pk_bf16_f32 v9, v17, v19
	global_store_dword v[10:11], v8, off
	global_store_dword v[2:3], v9, off
	v_pk_fma_f32 v[0:1], v[228:229], s[12:13], v[130:131] op_sel_hi:[1,0,0]
	v_add_u32_e32 v8, 0x90, v168
	v_add_u32_e32 v9, 0x91, v168
	v_rsq_f32_e32 v0, v0
	v_rsq_f32_e32 v1, v1
	v_mad_i64_i32 v[10:11], s[2:3], v8, s8, v[128:129]
	v_mad_i64_i32 v[2:3], s[2:3], v9, s8, v[128:129]
	v_pk_mul_f32 v[16:17], v[36:37], v[0:1]
	v_pk_mul_f32 v[18:19], v[32:33], v[0:1]
	v_pk_mul_f32 v[136:137], v[44:45], v[0:1]
	v_pk_mul_f32 v[138:139], v[40:41], v[0:1]
	v_mul_f32_e32 v140, 0xbfb8aa3b, v16
	v_mul_f32_e32 v141, 0xbfb8aa3b, v17
	v_mul_f32_e32 v142, 0xbfb8aa3b, v18
	v_mul_f32_e32 v143, 0xbfb8aa3b, v19
	v_exp_f32_e32 v140, v140
	v_exp_f32_e32 v141, v141
	v_exp_f32_e32 v142, v142
	v_exp_f32_e32 v143, v143
	v_add_f32_e32 v140, 1.0, v140
	v_add_f32_e32 v141, 1.0, v141
	v_add_f32_e32 v142, 1.0, v142
	v_add_f32_e32 v143, 1.0, v143
	v_rcp_f32_e32 v140, v140
	v_rcp_f32_e32 v141, v141
	v_rcp_f32_e32 v142, v142
	v_rcp_f32_e32 v143, v143
	s_nop 0
	v_pk_mul_f32 v[16:17], v[16:17], v[140:141]
	v_pk_mul_f32 v[18:19], v[18:19], v[142:143]
	v_pk_mul_f32 v[16:17], v[136:137], v[16:17]
	v_pk_mul_f32 v[18:19], v[138:139], v[18:19]
	v_cvt_pk_bf16_f32 v8, v16, v18
	v_cvt_pk_bf16_f32 v9, v17, v19
	global_store_dword v[10:11], v8, off
	global_store_dword v[2:3], v9, off
	v_pk_fma_f32 v[0:1], v[230:231], s[12:13], v[130:131] op_sel_hi:[1,0,0]
	v_add_u32_e32 v8, 0x92, v168
	v_add_u32_e32 v9, 0x93, v168
	v_rsq_f32_e32 v0, v0
	v_rsq_f32_e32 v1, v1
	v_mad_i64_i32 v[10:11], s[2:3], v8, s8, v[128:129]
	v_mad_i64_i32 v[2:3], s[2:3], v9, s8, v[128:129]
	v_pk_mul_f32 v[16:17], v[38:39], v[0:1]
	v_pk_mul_f32 v[18:19], v[34:35], v[0:1]
	v_pk_mul_f32 v[136:137], v[46:47], v[0:1]
	v_pk_mul_f32 v[138:139], v[42:43], v[0:1]
	v_mul_f32_e32 v140, 0xbfb8aa3b, v16
	v_mul_f32_e32 v141, 0xbfb8aa3b, v17
	v_mul_f32_e32 v142, 0xbfb8aa3b, v18
	v_mul_f32_e32 v143, 0xbfb8aa3b, v19
	v_exp_f32_e32 v140, v140
	v_exp_f32_e32 v141, v141
	v_exp_f32_e32 v142, v142
	v_exp_f32_e32 v143, v143
	v_add_f32_e32 v140, 1.0, v140
	v_add_f32_e32 v141, 1.0, v141
	v_add_f32_e32 v142, 1.0, v142
	v_add_f32_e32 v143, 1.0, v143
	v_rcp_f32_e32 v140, v140
	v_rcp_f32_e32 v141, v141
	v_rcp_f32_e32 v142, v142
	v_rcp_f32_e32 v143, v143
	s_nop 0
	v_pk_mul_f32 v[16:17], v[16:17], v[140:141]
	v_pk_mul_f32 v[18:19], v[18:19], v[142:143]
	v_pk_mul_f32 v[16:17], v[136:137], v[16:17]
	v_pk_mul_f32 v[18:19], v[138:139], v[18:19]
	v_cvt_pk_bf16_f32 v8, v16, v18
	v_cvt_pk_bf16_f32 v9, v17, v19
	global_store_dword v[10:11], v8, off
	global_store_dword v[2:3], v9, off
	v_pk_fma_f32 v[0:1], v[232:233], s[12:13], v[130:131] op_sel_hi:[1,0,0]
	v_add_u32_e32 v8, 0xa0, v168
	v_add_u32_e32 v9, 0xa1, v168
	v_rsq_f32_e32 v0, v0
	v_rsq_f32_e32 v1, v1
	v_mad_i64_i32 v[10:11], s[2:3], v8, s8, v[128:129]
	v_mad_i64_i32 v[2:3], s[2:3], v9, s8, v[128:129]
	v_pk_mul_f32 v[16:17], v[20:21], v[0:1]
	v_pk_mul_f32 v[18:19], v[240:241], v[0:1]
	v_pk_mul_f32 v[136:137], v[244:245], v[0:1]
	v_pk_mul_f32 v[138:139], v[24:25], v[0:1]
	v_mul_f32_e32 v140, 0xbfb8aa3b, v16
	v_mul_f32_e32 v141, 0xbfb8aa3b, v17
	v_mul_f32_e32 v142, 0xbfb8aa3b, v18
	v_mul_f32_e32 v143, 0xbfb8aa3b, v19
	v_exp_f32_e32 v140, v140
	v_exp_f32_e32 v141, v141
; __device__ __forceinline__ u32 pack2(float a, float b) { return (u32)f2bf(a) | ((u32)f2bf(b) << 16); }
; __device__ __forceinline__ float sigmoidf_(float x) { return __builtin_amdgcn_rcpf(1.f + __expf(-x)); }
; __device__ __forceinline__ void gemm_tile(const GemmArgs& ga, int wgid, int next_wgid, bool prefetched, u16* shm, unsigned char* ws, int wv_) {
;     ...
;   if (epi == EPI_SWIGLU) {
;     const int oc = pn * HALF + (wc * 16 + fr) * 2;
;     float sc[2][4][4];
;     _Pragma("unroll") for (int ai = 0; ai < 2; ++ai)
;       _Pragma("unroll") for (int m = 0; m < 4; ++m)
;         _Pragma("unroll") for (int j = 0; j < 4; ++j) sc[ai][m][j] = e_ss[rbase + ai * HALF + m * 16 + j];
;     _Pragma("unroll") for (int ai = 0; ai < 2; ++ai)
;       _Pragma("unroll") for (int m = 0; m < 4; ++m)
;         _Pragma("unroll") for (int j = 0; j < 4; ++j) {
;           int row = rbase + ai * HALF + m * 16 + j;
;           float s = rsqrtf(sc[ai][m][j] * (1.f / D_) + 1e-6f);
;           float h2[2];
;           _Pragma("unroll") for (int n = 0; n < 2; ++n) {
;             float a1 = acc[ai][0][m][n][j] * s, a3 = acc[ai][1][m][n][j] * s;
;             h2[n] = a1 * sigmoidf_(a1) * a3;
;           }
;           *(u32*)(e_outb + (size_t)row * F_ + oc) = pack2(h2[0], h2[1]);
;         }
	v_exp_f32_e32 v142, v142
	v_exp_f32_e32 v143, v143
	v_add_f32_e32 v140, 1.0, v140
	v_add_f32_e32 v141, 1.0, v141
	v_add_f32_e32 v142, 1.0, v142
	v_add_f32_e32 v143, 1.0, v143
	v_rcp_f32_e32 v140, v140
	v_rcp_f32_e32 v141, v141
	v_rcp_f32_e32 v142, v142
	v_rcp_f32_e32 v143, v143
	s_nop 0
	v_pk_mul_f32 v[16:17], v[16:17], v[140:141]
	v_pk_mul_f32 v[18:19], v[18:19], v[142:143]
	v_pk_mul_f32 v[16:17], v[136:137], v[16:17]
	v_pk_mul_f32 v[18:19], v[138:139], v[18:19]
	v_cvt_pk_bf16_f32 v8, v16, v18
	v_cvt_pk_bf16_f32 v9, v17, v19
	global_store_dword v[10:11], v8, off
	global_store_dword v[2:3], v9, off
	v_pk_fma_f32 v[0:1], v[234:235], s[12:13], v[130:131] op_sel_hi:[1,0,0]
	v_add_u32_e32 v8, 0xa2, v168
	v_add_u32_e32 v9, 0xa3, v168
	v_rsq_f32_e32 v0, v0
	v_rsq_f32_e32 v1, v1
	v_mad_i64_i32 v[10:11], s[2:3], v8, s8, v[128:129]
	v_mad_i64_i32 v[2:3], s[2:3], v9, s8, v[128:129]
	v_pk_mul_f32 v[16:17], v[22:23], v[0:1]
	v_pk_mul_f32 v[18:19], v[242:243], v[0:1]
	v_pk_mul_f32 v[136:137], v[246:247], v[0:1]
	v_pk_mul_f32 v[138:139], v[26:27], v[0:1]
	v_mul_f32_e32 v140, 0xbfb8aa3b, v16
	v_mul_f32_e32 v141, 0xbfb8aa3b, v17
	v_mul_f32_e32 v142, 0xbfb8aa3b, v18
	v_mul_f32_e32 v143, 0xbfb8aa3b, v19
	v_exp_f32_e32 v140, v140
	v_exp_f32_e32 v141, v141
	v_exp_f32_e32 v142, v142
	v_exp_f32_e32 v143, v143
	v_add_f32_e32 v140, 1.0, v140
	v_add_f32_e32 v141, 1.0, v141
	v_add_f32_e32 v142, 1.0, v142
	v_add_f32_e32 v143, 1.0, v143
	v_rcp_f32_e32 v140, v140
	v_rcp_f32_e32 v141, v141
	v_rcp_f32_e32 v142, v142
	v_rcp_f32_e32 v143, v143
	s_nop 0
	v_pk_mul_f32 v[16:17], v[16:17], v[140:141]
	v_pk_mul_f32 v[18:19], v[18:19], v[142:143]
	v_pk_mul_f32 v[16:17], v[136:137], v[16:17]
	v_pk_mul_f32 v[18:19], v[138:139], v[18:19]
	v_cvt_pk_bf16_f32 v8, v16, v18
	v_cvt_pk_bf16_f32 v9, v17, v19
	global_store_dword v[10:11], v8, off
	global_store_dword v[2:3], v9, off
	v_pk_fma_f32 v[0:1], v[236:237], s[12:13], v[130:131] op_sel_hi:[1,0,0]
	v_add_u32_e32 v8, 0xb0, v168
	v_add_u32_e32 v9, 0xb1, v168
	v_rsq_f32_e32 v0, v0
	v_rsq_f32_e32 v1, v1
	v_mad_i64_i32 v[10:11], s[2:3], v8, s8, v[128:129]
	v_mad_i64_i32 v[2:3], s[2:3], v9, s8, v[128:129]
	v_pk_mul_f32 v[16:17], v[204:205], v[0:1]
	v_pk_mul_f32 v[18:19], v[182:183], v[0:1]
	v_pk_mul_f32 v[136:137], v[12:13], v[0:1]
	v_pk_mul_f32 v[138:139], v[4:5], v[0:1]
	v_mul_f32_e32 v140, 0xbfb8aa3b, v16
	v_mul_f32_e32 v141, 0xbfb8aa3b, v17
	v_mul_f32_e32 v142, 0xbfb8aa3b, v18
	v_mul_f32_e32 v143, 0xbfb8aa3b, v19
	v_exp_f32_e32 v140, v140
	v_exp_f32_e32 v141, v141
	v_exp_f32_e32 v142, v142
	v_exp_f32_e32 v143, v143
	v_add_f32_e32 v140, 1.0, v140
	v_add_f32_e32 v141, 1.0, v141
	v_add_f32_e32 v142, 1.0, v142
	v_add_f32_e32 v143, 1.0, v143
	v_rcp_f32_e32 v140, v140
	v_rcp_f32_e32 v141, v141
	v_rcp_f32_e32 v142, v142
	v_rcp_f32_e32 v143, v143
	s_nop 0
	v_pk_mul_f32 v[16:17], v[16:17], v[140:141]
	v_pk_mul_f32 v[18:19], v[18:19], v[142:143]
	v_pk_mul_f32 v[16:17], v[136:137], v[16:17]
	v_pk_mul_f32 v[18:19], v[138:139], v[18:19]
	v_cvt_pk_bf16_f32 v8, v16, v18
	v_cvt_pk_bf16_f32 v9, v17, v19
	global_store_dword v[10:11], v8, off
	global_store_dword v[2:3], v9, off
	v_pk_fma_f32 v[0:1], v[238:239], s[12:13], v[130:131] op_sel_hi:[1,0,0]
	v_add_u32_e32 v8, 0xb2, v168
	v_add_u32_e32 v9, 0xb3, v168
	v_rsq_f32_e32 v0, v0
	v_rsq_f32_e32 v1, v1
	v_mad_i64_i32 v[10:11], s[2:3], v8, s8, v[128:129]
	v_mad_i64_i32 v[2:3], s[2:3], v9, s8, v[128:129]
	v_pk_mul_f32 v[16:17], v[206:207], v[0:1]
	v_pk_mul_f32 v[18:19], v[184:185], v[0:1]
	v_pk_mul_f32 v[136:137], v[14:15], v[0:1]
	v_pk_mul_f32 v[138:139], v[6:7], v[0:1]
	v_mul_f32_e32 v140, 0xbfb8aa3b, v16
	v_mul_f32_e32 v141, 0xbfb8aa3b, v17
	v_mul_f32_e32 v142, 0xbfb8aa3b, v18
	v_mul_f32_e32 v143, 0xbfb8aa3b, v19
	v_exp_f32_e32 v140, v140
	v_exp_f32_e32 v141, v141
	v_exp_f32_e32 v142, v142
	v_exp_f32_e32 v143, v143
	v_add_f32_e32 v140, 1.0, v140
	v_add_f32_e32 v141, 1.0, v141
	v_add_f32_e32 v142, 1.0, v142
	v_add_f32_e32 v143, 1.0, v143
	v_rcp_f32_e32 v140, v140
	v_rcp_f32_e32 v141, v141
	v_rcp_f32_e32 v142, v142
	v_rcp_f32_e32 v143, v143
	s_nop 0
	v_pk_mul_f32 v[16:17], v[16:17], v[140:141]
	v_pk_mul_f32 v[18:19], v[18:19], v[142:143]
	v_pk_mul_f32 v[16:17], v[136:137], v[16:17]
	v_pk_mul_f32 v[18:19], v[138:139], v[18:19]
	v_cvt_pk_bf16_f32 v8, v16, v18
	v_cvt_pk_bf16_f32 v9, v17, v19
	global_store_dword v[10:11], v8, off
	global_store_dword v[2:3], v9, off
	s_branch .LBB0_501
